# GEMM phases: workgroups of XCDs 4-7 start 4 us later so the two chip halves' per-tile epilogue store bursts do not collide at HBM
# baseline (speedup 1.0000x reference)
; #define PG8_STAGE(bufoff, gbase, voff) do { _Pragma("unroll") for (int _i = 0; _i < 2; ++_i) \
;         __builtin_amdgcn_global_load_lds((const unsigned*)((const char*)(gbase) + (voff)[_i]), (PG8_LAS unsigned*)(lds + (bufoff) + ldsw + _i * 8192), 16, 0, 0); } while (0)
; #define PG8_WAIT_V(n) asm volatile("s_waitcnt vmcnt(" #n ")" ::: "memory")
; #define PG8_BAR __builtin_amdgcn_s_barrier()
; template <class Epi, class Sched, bool ALIGN_EPI = false, bool SP2 = false>
; __device__ __forceinline__ void gemm_phase(PG8_LAS unsigned char* lds, const Gemm g, const Sched& S, const Epi& E) {
;     const int tid = threadIdx.x, wid = __builtin_amdgcn_readfirstlane(tid >> 6), lane = tid & 63, wr = wid >> 2, wc = wid & 3, fr = lane & 15, fq = lane >> 4;
;     const int K = g.K, nt = K / BK;
;     unsigned voffA[2], voffB[2];
; #pragma unroll
;     for (int i = 0; i < 2; ++i) { int R, C; stage_rc(tid * 16 + i * 8192, R, C); const int Rb = Epi::PERM ? ((R & ~31) + perm32(R & 31)) : R;
;         voffA[i] = (unsigned)(R * K + C) * 2u; voffB[i] = (unsigned)(Rb * K + C) * 2u; }
;     const size_t kstep = (size_t)(BK * 2);
;     const size_t hstep = (size_t)HALF * K * 2;
;     const size_t tstep = 2 * hstep;
;     const unsigned ldsw = (unsigned)wid * 1024u;
;     const int aoff = lds_byte(wr * 64 + fr, fq * 8), boff = lds_byte(wc * 32 + fr, fq * 8);
;     ...
;     Unit cur, nxt; int ui = 0;
;     if (!S.next(0, cur)) return;
;     f32x4 acc[2][2][4][2];
; #pragma unroll
;     for (int a = 0; a < 2; ++a)
; #pragma unroll
;         for (int b = 0; b < 2; ++b)
; #pragma unroll
;             for (int m = 0; m < 4; ++m)
; #pragma unroll
;                 for (int n = 0; n < 2; ++n) acc[a][b][m][n] = (f32x4){0.f, 0.f, 0.f, 0.f};
;     bf16x8 At[4][2], B0[2][2], B1[2][2];
;     const char* cA = (const char*)g.A + (size_t)cur.pm * tstep; const char* cB = (const char*)g.Bt + (size_t)cur.pn * tstep;
;     S.a_ready(cur);
;     if constexpr (SP2) {
;         PG8_STAGE(PG8_SB(0, 0), cB, voffB); PG8_STAGE(PG8_SB(0, 1), cB + hstep, voffB); PG8_STAGE(PG8_SA(0, 0), cA, voffA); PG8_STAGE(PG8_SA(0, 1), cA + hstep, voffA);
;         if (wr == 1) PG8_BAR;
;         PG8_WAIT_V(2); PG8_BAR;
;         PG8_STAGE(PG8_SB(1, 0), cB + kstep, voffB); PG8_STAGE(PG8_SA(1, 0), cA + kstep, voffA); PG8_STAGE(PG8_SB(1, 1), cB + hstep + kstep, voffB);
;         PG8_WAIT_V(6); PG8_BAR;
.LBB0_129:
	s_cmp_lt_i32 s80, 2
	s_cselect_b64 s[0:1], -1, 0
	s_add_u32 s24, s22, 0xb800000
	s_addc_u32 s25, s23, 0
	s_and_b64 s[4:5], s[0:1], s[4:5]
	s_mov_b32 s19, s84
	s_andn2_b64 vcc, exec, s[4:5]
	s_cbranch_vccnz .LBB0_146
	s_cmpk_gt_i32 s84, 0x6bf
	v_readfirstlane_b32 s1, v146
	s_cbranch_scc1 .LBB0_146
	s_bitcmp1_b32 s84, 2
	s_cbranch_scc0 .Lstag1_done
	s_memrealtime s[98:99]
	s_waitcnt lgkmcnt(0)
	s_mov_b32 s100, s98
.Lstag1_l:
	s_memrealtime s[98:99]
	s_waitcnt lgkmcnt(0)
	s_sub_u32 s98, s98, s100
	s_cmp_lt_u32 s98, 400
	s_cbranch_scc1 .Lstag1_l
.Lstag1_done:
	v_lshrrev_b32_e32 v0, 5, v146
	v_lshrrev_b32_e32 v2, 1, v146
	v_and_b32_e32 v0, 4, v0
	v_bfe_u32 v1, v146, 2, 2
	v_and_b32_e32 v11, 24, v2
	v_or3_b32 v0, v0, v1, v11
	v_lshlrev_b32_e32 v1, 4, v146
	v_add_u32_e32 v8, 0x2000, v1
	v_lshrrev_b32_e32 v2, 7, v8
	s_movk_i32 s0, 0xe0
	v_and_b32_e32 v4, 32, v146
	v_and_or_b32 v3, v2, s0, v0
	v_bitop3_b32 v9, v1, v4, 48 bitop3:0x6c
	v_and_b32_e32 v10, 64, v146
	v_bfe_u32 v12, v146, 2, 4
	s_movk_i32 s0, 0xf0
	v_or_b32_e32 v1, v9, v10
	v_and_or_b32 v2, v2, s0, v12
	v_lshl_or_b32 v130, v2, 12, v1
	v_lshrrev_b32_e32 v2, 3, v146
	s_movk_i32 s0, 0x60
	v_and_or_b32 v0, v2, s0, v0
	s_movk_i32 s0, 0x70
	s_ashr_i32 s33, s84, 31
	v_lshl_or_b32 v132, v0, 12, v1
	v_and_or_b32 v0, v2, s0, v12
	s_lshr_b32 s0, s33, 29
	s_add_i32 s0, s84, s0
	s_lshr_b32 s8, s1, 6
	s_ashr_i32 s6, s0, 3
	s_and_b32 s0, s0, -8
	s_lshr_b32 s10, s1, 8
	s_lshl_b32 s3, s8, 10
	s_sub_i32 s0, s84, s0
	s_cmp_lt_i32 s0, 0
	s_movk_i32 s40, 0xd9
	s_cselect_b32 s7, s40, 0xd8
	s_mul_i32 s0, s7, s0
	s_add_i32 s0, s0, s6
	s_mul_hi_i32 s6, s0, 0x4bda12f7
	s_lshr_b32 s7, s6, 31
	s_ashr_i32 s6, s6, 6
	s_add_i32 s6, s6, s7
	s_lshl_b32 s7, s6, 3
	s_mulk_i32 s6, 0xd8
	s_sub_i32 s6, s0, s6
	s_sext_i32_i16 s0, s6
	s_bfe_u32 s0, s0, 0x3001c
	s_add_i32 s9, s6, s0
	s_sext_i32_i16 s0, s9
	s_and_b32 s9, s9, 0xfff8
	s_sub_i32 s6, s6, s9
	s_sext_i32_i16 s6, s6
	s_lshr_b32 s0, s0, 3
	s_add_i32 s30, s7, s6
	s_ashr_i32 s31, s30, 31
	s_bfe_i64 s[12:13], s[0:1], 0x100000
	s_lshl_b64 s[6:7], s[30:31], 20
	s_lshl_b64 s[12:13], s[12:13], 20
	v_readlane_b32 s14, v231, 18
	v_readlane_b32 s15, v231, 19
	s_add_u32 s36, s14, s12
	s_addc_u32 s37, s15, s13
	s_add_i32 s31, s3, 0
	s_add_i32 m0, s31, 0x10000
	v_lshl_or_b32 v128, v3, 12, v1
	global_load_lds_dwordx4 v132, s[36:37]
	s_add_i32 m0, s31, 0x12000
	s_add_u32 s12, s36, 0x80000
	global_load_lds_dwordx4 v128, s[36:37]
	s_addc_u32 s13, s37, 0
	s_add_i32 m0, s31, 0x14000
	v_lshl_or_b32 v134, v0, 12, v1
	global_load_lds_dwordx4 v132, s[12:13]
	s_add_i32 m0, s31, 0x16000
	s_add_u32 s34, s96, s6
	s_addc_u32 s35, s97, s7
	s_add_i32 s41, s31, 0x2000
	global_load_lds_dwordx4 v128, s[12:13]
	s_mov_b32 m0, s31
	s_add_u32 s6, s34, 0x80000
	global_load_lds_dwordx4 v134, s[34:35]
	s_mov_b32 m0, s41
	s_addc_u32 s7, s35, 0
	s_add_i32 s42, s31, 0x4000
	global_load_lds_dwordx4 v130, s[34:35]
	s_mov_b32 m0, s42
	s_add_i32 s43, s31, 0x6000
	global_load_lds_dwordx4 v134, s[6:7]
	s_mov_b32 m0, s43
	v_mov_b32_e32 v133, 0
	global_load_lds_dwordx4 v130, s[6:7]
	v_mov_b32_e32 v129, v133
	v_mov_b32_e32 v135, v133
	v_mov_b32_e32 v131, v133
	s_cmp_eq_u32 s10, 1
	s_mov_b32 s44, 0
	v_lshl_add_u64 v[6:7], s[36:37], 0, v[132:133]
	v_lshl_add_u64 v[4:5], s[36:37], 0, v[128:129]
	v_lshl_add_u64 v[0:1], s[34:35], 0, v[134:135]
	s_cselect_b64 s[6:7], -1, 0
	s_cmp_lg_u32 s10, 1
	v_lshl_add_u64 v[2:3], s[34:35], 0, v[130:131]
	s_cbranch_scc1 .LBB0_133
	s_barrier

; #define SEAM(k) do { if (IN(k) && IN((k) + 1)) { if ((k) == 0) { cg::this_grid().sync(); bar = xcd_barrier_post(barw, MISC); } else { xcd_barrier(bar); } } } while (0)
; template <class Epi, class Sched, bool ALIGN_EPI = false, bool SP2 = false>
; __device__ __forceinline__ void gemm_phase(PG8_LAS unsigned char* lds, const Gemm g, const Sched& S, const Epi& E) {
;     ...
;     if (!S.next(0, cur)) return;
; __global__ void __launch_bounds__(NTHR, 2) fwd(Args args) {
;     ...
;     if (IN(4)) { gemm_res(F, XB, WOUT, DM, F.in[0], F.out); } SEAM(4);
.LBB0_590:
	s_cmp_lt_i32 s80, 5
	s_cselect_b64 s[4:5], -1, 0
	s_and_b64 s[4:5], s[4:5], s[0:1]
	s_andn2_b64 vcc, exec, s[4:5]
	s_cbranch_vccnz .LBB0_615
	s_cmpk_gt_i32 s84, 0x1ff
	v_readfirstlane_b32 s10, v146
	s_cbranch_scc1 .LBB0_615
	s_bitcmp1_b32 s84, 2
	s_cbranch_scc0 .Lstag4_done
	s_memrealtime s[98:99]
	s_waitcnt lgkmcnt(0)
	s_mov_b32 s100, s98

;     __host__ __device__ bool next(int i, Unit& u) const {
;         const long L = (long)i * G + c; if (L >= nwg) return false;
;         int wgid = (int)L; { const int q = nwg / NXCD, r = nwg % NXCD, xcd = wgid % NXCD, off = wgid / NXCD; wgid = (xcd < r ? xcd * (q + 1) : r * (q + 1) + (xcd - r) * q) + off; }
;         const int nig = WGM * nN, gid = wgid / nig, fm = gid * WGM, gsz = (nM - fm) < WGM ? (nM - fm) : WGM;
;         u.pm = fm + ((wgid % nig) % gsz); u.pn = (wgid % nig) / gsz; return true;
.Lstag4_done:
	s_ashr_i32 s3, s84, 31
	s_lshr_b32 s0, s3, 29
	s_add_i32 s7, s84, s0
	s_and_b32 s0, s7, -8
	s_sub_i32 s8, s84, s0
	s_cmp_gt_i32 s8, -1
	s_cbranch_scc0 .LBB0_594
	s_lshl_b32 s6, s8, 6
	s_cbranch_execz .LBB0_595
	s_branch .LBB0_596

; #define SEAM(k) do { if (IN(k) && IN((k) + 1)) { if ((k) == 0) { cg::this_grid().sync(); bar = xcd_barrier_post(barw, MISC); } else { xcd_barrier(bar); } } } while (0)
; template <class Epi, class Sched, bool ALIGN_EPI = false, bool SP2 = false>
; __device__ __forceinline__ void gemm_phase(PG8_LAS unsigned char* lds, const Gemm g, const Sched& S, const Epi& E) {
;     ...
;     if (!S.next(0, cur)) return;
; __global__ void __launch_bounds__(NTHR, 2) fwd(Args args) {
;     ...
;     if (IN(6)) { gemm_bf16(F, XB, W1, DFF, DM, BIG, DFF, true); } SEAM(6);
.LBB0_723:
	s_cmp_lt_i32 s80, 7
	s_cselect_b64 s[4:5], -1, 0
	s_and_b64 s[4:5], s[4:5], s[0:1]
	s_andn2_b64 vcc, exec, s[4:5]
	s_cbranch_vccnz .LBB0_740
	s_cmpk_gt_i32 s84, 0x7ff
	v_readfirstlane_b32 s1, v146
	s_cbranch_scc1 .LBB0_740
	s_bitcmp1_b32 s84, 2
	s_cbranch_scc0 .Lstag6_done
	s_memrealtime s[98:99]
	s_waitcnt lgkmcnt(0)
	s_mov_b32 s100, s98

; #define PG8_STAGE(bufoff, gbase, voff) do { _Pragma("unroll") for (int _i = 0; _i < 2; ++_i) \
;         __builtin_amdgcn_global_load_lds((const unsigned*)((const char*)(gbase) + (voff)[_i]), (PG8_LAS unsigned*)(lds + (bufoff) + ldsw + _i * 8192), 16, 0, 0); } while (0)
; #define PG8_WAIT_V(n) asm volatile("s_waitcnt vmcnt(" #n ")" ::: "memory")
; #define PG8_BAR __builtin_amdgcn_s_barrier()
; template <class Epi, class Sched, bool ALIGN_EPI = false, bool SP2 = false>
; __device__ __forceinline__ void gemm_phase(PG8_LAS unsigned char* lds, const Gemm g, const Sched& S, const Epi& E) {
;     const int tid = threadIdx.x, wid = __builtin_amdgcn_readfirstlane(tid >> 6), lane = tid & 63, wr = wid >> 2, wc = wid & 3, fr = lane & 15, fq = lane >> 4;
;     const int K = g.K, nt = K / BK;
;     unsigned voffA[2], voffB[2];
; #pragma unroll
;     for (int i = 0; i < 2; ++i) { int R, C; stage_rc(tid * 16 + i * 8192, R, C); const int Rb = Epi::PERM ? ((R & ~31) + perm32(R & 31)) : R;
;         voffA[i] = (unsigned)(R * K + C) * 2u; voffB[i] = (unsigned)(Rb * K + C) * 2u; }
;     const size_t kstep = (size_t)(BK * 2);
;     const size_t hstep = (size_t)HALF * K * 2;
;     const size_t tstep = 2 * hstep;
;     const unsigned ldsw = (unsigned)wid * 1024u;
;     const int aoff = lds_byte(wr * 64 + fr, fq * 8), boff = lds_byte(wc * 32 + fr, fq * 8);
;     ...
;     Unit cur, nxt; int ui = 0;
;     if (!S.next(0, cur)) return;
;     f32x4 acc[2][2][4][2];
; #pragma unroll
;     for (int a = 0; a < 2; ++a)
; #pragma unroll
;         for (int b = 0; b < 2; ++b)
; #pragma unroll
;             for (int m = 0; m < 4; ++m)
; #pragma unroll
;                 for (int n = 0; n < 2; ++n) acc[a][b][m][n] = (f32x4){0.f, 0.f, 0.f, 0.f};
;     bf16x8 At[4][2], B0[2][2], B1[2][2];
;     const char* cA = (const char*)g.A + (size_t)cur.pm * tstep; const char* cB = (const char*)g.Bt + (size_t)cur.pn * tstep;
;     S.a_ready(cur);
;     if constexpr (SP2) {
;         PG8_STAGE(PG8_SB(0, 0), cB, voffB); PG8_STAGE(PG8_SB(0, 1), cB + hstep, voffB); PG8_STAGE(PG8_SA(0, 0), cA, voffA); PG8_STAGE(PG8_SA(0, 1), cA + hstep, voffA);
;         if (wr == 1) PG8_BAR;
;         PG8_WAIT_V(2); PG8_BAR;
;         PG8_STAGE(PG8_SB(1, 0), cB + kstep, voffB); PG8_STAGE(PG8_SA(1, 0), cA + kstep, voffA); PG8_STAGE(PG8_SB(1, 1), cB + hstep + kstep, voffB);
;         PG8_WAIT_V(6); PG8_BAR;
.Lstag6_done:
	v_lshrrev_b32_e32 v0, 5, v146
	v_lshrrev_b32_e32 v2, 1, v146
	v_and_b32_e32 v0, 4, v0
	v_bfe_u32 v1, v146, 2, 2
	v_and_b32_e32 v11, 24, v2
	v_or3_b32 v0, v0, v1, v11
	v_lshlrev_b32_e32 v1, 4, v146
	s_waitcnt lgkmcnt(0)
	v_add_u32_e32 v8, 0x2000, v1
	v_lshrrev_b32_e32 v2, 7, v8
	s_movk_i32 s0, 0xe0
	v_and_b32_e32 v4, 32, v146
	v_and_or_b32 v3, v2, s0, v0
	v_bitop3_b32 v9, v1, v4, 48 bitop3:0x6c
	v_and_b32_e32 v10, 64, v146
	v_bfe_u32 v12, v146, 2, 4
	s_movk_i32 s0, 0xf0
	v_or_b32_e32 v1, v9, v10
	v_and_or_b32 v2, v2, s0, v12
	s_waitcnt vmcnt(0)
	v_lshl_or_b32 v130, v2, 12, v1
	v_lshrrev_b32_e32 v2, 3, v146
	s_movk_i32 s0, 0x60
	v_and_or_b32 v0, v2, s0, v0
	s_movk_i32 s0, 0x70
	s_ashr_i32 s33, s84, 31
	v_lshl_or_b32 v132, v0, 12, v1
	v_and_or_b32 v0, v2, s0, v12
	s_lshr_b32 s0, s33, 29
	s_add_i32 s0, s84, s0
	s_lshr_b32 s8, s1, 6
	s_ashr_i32 s6, s0, 3
	s_and_b32 s0, s0, -8
	s_lshr_b32 s10, s1, 8
	s_lshl_b32 s3, s8, 10
	s_sub_i32 s0, s84, s0
	s_cmp_lt_i32 s0, 0
	s_movk_i32 s48, 0x101
	s_cselect_b32 s7, s48, 0x100
	s_mul_i32 s0, s7, s0
	s_add_i32 s0, s0, s6
	s_ashr_i32 s6, s0, 31
	s_lshr_b32 s6, s6, 24
	s_add_i32 s6, s0, s6
	s_ashr_i32 s7, s6, 8
	s_and_b32 s6, s6, 0xffffff00
	s_sub_i32 s6, s0, s6
	s_sext_i32_i16 s0, s6
	s_bfe_u32 s0, s0, 0x3001c
	s_add_i32 s9, s6, s0
	s_sext_i32_i16 s0, s9
	s_and_b32 s9, s9, 0xfff8
	s_sub_i32 s6, s6, s9
	s_lshl_b32 s7, s7, 3
	s_sext_i32_i16 s6, s6
	s_lshr_b32 s0, s0, 3
	s_add_i32 s40, s7, s6
	s_ashr_i32 s41, s40, 31
	s_bfe_i64 s[12:13], s[0:1], 0x100000
	s_lshl_b64 s[6:7], s[40:41], 20
	s_lshl_b64 s[12:13], s[12:13], 20
	v_readlane_b32 s14, v231, 22
	v_readlane_b32 s15, v231, 23
	s_add_u32 s44, s14, s12
	s_addc_u32 s45, s15, s13
	s_add_i32 s41, s3, 0
	s_add_i32 m0, s41, 0x10000
	v_lshl_or_b32 v128, v3, 12, v1
	global_load_lds_dwordx4 v132, s[44:45]
	s_add_i32 m0, s41, 0x12000
	s_add_u32 s12, s44, 0x80000
	global_load_lds_dwordx4 v128, s[44:45]
	s_addc_u32 s13, s45, 0
	s_add_i32 m0, s41, 0x14000
	v_lshl_or_b32 v134, v0, 12, v1
	global_load_lds_dwordx4 v132, s[12:13]
	s_add_i32 m0, s41, 0x16000
	s_add_u32 s42, s96, s6
	s_addc_u32 s43, s97, s7
	s_add_i32 s49, s41, 0x2000
	global_load_lds_dwordx4 v128, s[12:13]
	s_mov_b32 m0, s41
	s_add_u32 s6, s42, 0x80000
	global_load_lds_dwordx4 v134, s[42:43]
	s_mov_b32 m0, s49
	s_addc_u32 s7, s43, 0
	s_add_i32 s50, s41, 0x4000
	global_load_lds_dwordx4 v130, s[42:43]
	s_mov_b32 m0, s50
	s_add_i32 s51, s41, 0x6000
	global_load_lds_dwordx4 v134, s[6:7]
	s_mov_b32 m0, s51
	v_mov_b32_e32 v133, 0
	global_load_lds_dwordx4 v130, s[6:7]
	v_mov_b32_e32 v129, v133
	v_mov_b32_e32 v135, v133
	v_mov_b32_e32 v131, v133
	s_cmp_eq_u32 s10, 1
	s_mov_b32 s52, 0
	v_lshl_add_u64 v[6:7], s[44:45], 0, v[132:133]
	v_lshl_add_u64 v[4:5], s[44:45], 0, v[128:129]
	v_lshl_add_u64 v[0:1], s[42:43], 0, v[134:135]
	s_cselect_b64 s[6:7], -1, 0
	s_cmp_lg_u32 s10, 1
	v_lshl_add_u64 v[2:3], s[42:43], 0, v[130:131]
	s_cbranch_scc1 .LBB0_727
	s_barrier

; #define SEAM(k) do { if (IN(k) && IN((k) + 1)) { if ((k) == 0) { cg::this_grid().sync(); bar = xcd_barrier_post(barw, MISC); } else { xcd_barrier(bar); } } } while (0)
; template <class Epi, class Sched, bool ALIGN_EPI = false, bool SP2 = false>
; __device__ __forceinline__ void gemm_phase(PG8_LAS unsigned char* lds, const Gemm g, const Sched& S, const Epi& E) {
;     ...
;     if (!S.next(0, cur)) return;
; __global__ void __launch_bounds__(NTHR, 2) fwd(Args args) {
;     ...
;     if (IN(7)) { gemm_res_ln(F, BIG, W2, DFF, F.out, F.in[6], F.in[7]); } SEAM(7);
.LBB0_790:
	s_cmp_lt_i32 s80, 8
	s_cselect_b64 s[4:5], -1, 0
	s_and_b64 s[4:5], s[4:5], s[0:1]
	s_andn2_b64 vcc, exec, s[4:5]
	s_cbranch_vccnz .LBB0_815
	s_cmpk_gt_i32 s84, 0x1ff
	v_readfirstlane_b32 s12, v146
	s_cbranch_scc1 .LBB0_815
	s_bitcmp1_b32 s84, 2
	s_cbranch_scc0 .Lstag7_done
	s_memrealtime s[98:99]
	s_waitcnt lgkmcnt(0)
	s_mov_b32 s100, s98

; #define PG8_LAS __attribute__((address_space(3)))
; #define SEAM(k) do { if (IN(k) && IN((k) + 1)) { if ((k) == 0) { cg::this_grid().sync(); bar = xcd_barrier_post(barw, MISC); } else { xcd_barrier(bar); } } } while (0)
; template <class Epi, class Sched, bool ALIGN_EPI = false, bool SP2 = false>
; __device__ __forceinline__ void gemm_phase(PG8_LAS unsigned char* lds, const Gemm g, const Sched& S, const Epi& E) {
;     ...
;     if (!S.next(0, cur)) return;
; __global__ void __launch_bounds__(NTHR, 2) fwd(Args args) {
;     ...
;     if (IN(9)) { pg8::Gemm g{XB, WIN, MTOK, ODD_IN, DM}; pg8::StaticOrder S; S.init(MTOK, ODD_IN, F.G, F.bid); pg8::EpiBf16HeadMajor E{BIG};
;         pg8::gemm_phase<pg8::EpiBf16HeadMajor, pg8::StaticOrder, PG8_ALIGN, PG8_SP2>((PG8_LAS unsigned char*)F.lds, g, S, E); } SEAM(9);
.LBB0_1002:
	s_cmp_lt_i32 s80, 10
	s_cselect_b64 s[4:5], -1, 0
	s_and_b64 s[4:5], s[4:5], s[0:1]
	s_andn2_b64 vcc, exec, s[4:5]
	s_cbranch_vccnz .LBB0_1019
	s_cmpk_gt_i32 s84, 0x5ff
	v_readfirstlane_b32 s1, v146
	s_cbranch_scc1 .LBB0_1019
	s_bitcmp1_b32 s84, 2
	s_cbranch_scc0 .Lstag9_done
	s_memrealtime s[98:99]
	s_waitcnt lgkmcnt(0)
	s_mov_b32 s100, s98

; #define PG8_STAGE(bufoff, gbase, voff) do { _Pragma("unroll") for (int _i = 0; _i < 2; ++_i) \
;         __builtin_amdgcn_global_load_lds((const unsigned*)((const char*)(gbase) + (voff)[_i]), (PG8_LAS unsigned*)(lds + (bufoff) + ldsw + _i * 8192), 16, 0, 0); } while (0)
; #define PG8_WAIT_V(n) asm volatile("s_waitcnt vmcnt(" #n ")" ::: "memory")
; #define PG8_BAR __builtin_amdgcn_s_barrier()
; template <class Epi, class Sched, bool ALIGN_EPI = false, bool SP2 = false>
; __device__ __forceinline__ void gemm_phase(PG8_LAS unsigned char* lds, const Gemm g, const Sched& S, const Epi& E) {
;     const int tid = threadIdx.x, wid = __builtin_amdgcn_readfirstlane(tid >> 6), lane = tid & 63, wr = wid >> 2, wc = wid & 3, fr = lane & 15, fq = lane >> 4;
;     const int K = g.K, nt = K / BK;
;     unsigned voffA[2], voffB[2];
; #pragma unroll
;     for (int i = 0; i < 2; ++i) { int R, C; stage_rc(tid * 16 + i * 8192, R, C); const int Rb = Epi::PERM ? ((R & ~31) + perm32(R & 31)) : R;
;         voffA[i] = (unsigned)(R * K + C) * 2u; voffB[i] = (unsigned)(Rb * K + C) * 2u; }
;     const size_t kstep = (size_t)(BK * 2);
;     const size_t hstep = (size_t)HALF * K * 2;
;     const size_t tstep = 2 * hstep;
;     const unsigned ldsw = (unsigned)wid * 1024u;
;     const int aoff = lds_byte(wr * 64 + fr, fq * 8), boff = lds_byte(wc * 32 + fr, fq * 8);
;     ...
;     Unit cur, nxt; int ui = 0;
;     if (!S.next(0, cur)) return;
;     f32x4 acc[2][2][4][2];
; #pragma unroll
;     for (int a = 0; a < 2; ++a)
; #pragma unroll
;         for (int b = 0; b < 2; ++b)
; #pragma unroll
;             for (int m = 0; m < 4; ++m)
; #pragma unroll
;                 for (int n = 0; n < 2; ++n) acc[a][b][m][n] = (f32x4){0.f, 0.f, 0.f, 0.f};
;     bf16x8 At[4][2], B0[2][2], B1[2][2];
;     const char* cA = (const char*)g.A + (size_t)cur.pm * tstep; const char* cB = (const char*)g.Bt + (size_t)cur.pn * tstep;
;     S.a_ready(cur);
;     if constexpr (SP2) {
;         PG8_STAGE(PG8_SB(0, 0), cB, voffB); PG8_STAGE(PG8_SB(0, 1), cB + hstep, voffB); PG8_STAGE(PG8_SA(0, 0), cA, voffA); PG8_STAGE(PG8_SA(0, 1), cA + hstep, voffA);
;         if (wr == 1) PG8_BAR;
;         PG8_WAIT_V(2); PG8_BAR;
;         PG8_STAGE(PG8_SB(1, 0), cB + kstep, voffB); PG8_STAGE(PG8_SA(1, 0), cA + kstep, voffA); PG8_STAGE(PG8_SB(1, 1), cB + hstep + kstep, voffB);
;         PG8_WAIT_V(6); PG8_BAR;
.Lstag9_done:
	v_lshrrev_b32_e32 v0, 5, v146
	v_lshrrev_b32_e32 v2, 1, v146
	v_and_b32_e32 v0, 4, v0
	v_bfe_u32 v1, v146, 2, 2
	v_and_b32_e32 v11, 24, v2
	v_or3_b32 v0, v0, v1, v11
	v_lshlrev_b32_e32 v1, 4, v146
	s_waitcnt lgkmcnt(0)
	v_add_u32_e32 v8, 0x2000, v1
	v_lshrrev_b32_e32 v2, 7, v8
	s_movk_i32 s0, 0xe0
	v_and_b32_e32 v4, 32, v146
	v_and_or_b32 v3, v2, s0, v0
	v_bitop3_b32 v9, v1, v4, 48 bitop3:0x6c
	v_and_b32_e32 v10, 64, v146
	v_bfe_u32 v12, v146, 2, 4
	s_movk_i32 s0, 0xf0
	v_or_b32_e32 v1, v9, v10
	v_and_or_b32 v2, v2, s0, v12
	s_waitcnt vmcnt(0)
	v_lshl_or_b32 v130, v2, 12, v1
	v_lshrrev_b32_e32 v2, 3, v146
	s_movk_i32 s0, 0x60
	v_and_or_b32 v0, v2, s0, v0
	s_movk_i32 s0, 0x70
	s_ashr_i32 s33, s84, 31
	v_lshl_or_b32 v132, v0, 12, v1
	v_and_or_b32 v0, v2, s0, v12
	s_lshr_b32 s0, s33, 29
	s_add_i32 s0, s84, s0
	s_lshr_b32 s8, s1, 6
	s_ashr_i32 s6, s0, 3
	s_and_b32 s0, s0, -8
	s_lshr_b32 s9, s1, 8
	s_lshl_b32 s3, s8, 10
	s_sub_i32 s0, s84, s0
	s_cmp_lt_i32 s0, 0
	s_movk_i32 s42, 0xc1
	s_cselect_b32 s7, s42, 0xc0
	s_mul_i32 s0, s0, s7
	s_add_i32 s0, s0, s6
	s_mul_hi_i32 s6, s0, 0x2aaaaaab
	s_lshr_b32 s7, s6, 31
	s_ashr_i32 s6, s6, 5
	s_add_i32 s6, s6, s7
	s_lshl_b32 s7, s6, 3
	s_mulk_i32 s6, 0xc0
	s_sub_i32 s6, s0, s6
	s_sext_i32_i16 s0, s6
	s_bfe_u32 s0, s0, 0x3001c
	s_add_i32 s10, s6, s0
	s_sext_i32_i16 s0, s10
	s_and_b32 s10, s10, 0xfff8
	s_sub_i32 s6, s6, s10
	s_sext_i32_i16 s6, s6
	s_lshr_b32 s0, s0, 3
	s_add_i32 s34, s7, s6
	s_ashr_i32 s35, s34, 31
	s_bfe_i64 s[10:11], s[0:1], 0x100000
	s_lshl_b64 s[6:7], s[34:35], 20
	s_lshl_b64 s[10:11], s[10:11], 20
	v_readlane_b32 s12, v231, 18
	v_readlane_b32 s13, v231, 19
	s_add_u32 s38, s12, s10
	s_addc_u32 s39, s13, s11
	s_add_i32 s43, s3, 0
	s_add_i32 m0, s43, 0x10000
	v_lshl_or_b32 v128, v3, 12, v1
	global_load_lds_dwordx4 v132, s[38:39]
	s_add_i32 m0, s43, 0x12000
	s_add_u32 s10, s38, 0x80000
	global_load_lds_dwordx4 v128, s[38:39]
	s_addc_u32 s11, s39, 0
	s_add_i32 m0, s43, 0x14000
	v_lshl_or_b32 v134, v0, 12, v1
	global_load_lds_dwordx4 v132, s[10:11]
	s_add_i32 m0, s43, 0x16000
	s_add_u32 s36, s96, s6
	s_addc_u32 s37, s97, s7
	s_add_i32 s44, s43, 0x2000
	global_load_lds_dwordx4 v128, s[10:11]
	s_mov_b32 m0, s43
	s_add_u32 s6, s36, 0x80000
	global_load_lds_dwordx4 v134, s[36:37]
	s_mov_b32 m0, s44
	s_addc_u32 s7, s37, 0
	s_add_i32 s45, s43, 0x4000
	global_load_lds_dwordx4 v130, s[36:37]
	s_mov_b32 m0, s45
	s_add_i32 s46, s43, 0x6000
	global_load_lds_dwordx4 v134, s[6:7]
	s_mov_b32 m0, s46
	v_mov_b32_e32 v137, 0
	global_load_lds_dwordx4 v130, s[6:7]
	v_mov_b32_e32 v133, v137
	v_mov_b32_e32 v129, v137
	v_mov_b32_e32 v135, v137
	v_mov_b32_e32 v131, v137
	s_cmp_eq_u32 s9, 1
	s_mov_b32 s47, 0
	v_lshl_add_u64 v[6:7], s[38:39], 0, v[132:133]
	v_lshl_add_u64 v[4:5], s[38:39], 0, v[128:129]
	v_lshl_add_u64 v[0:1], s[36:37], 0, v[134:135]
	s_cselect_b64 s[6:7], -1, 0
	s_cmp_lg_u32 s9, 1
	v_lshl_add_u64 v[2:3], s[36:37], 0, v[130:131]
	s_cbranch_scc1 .LBB0_1006
	s_barrier

; #define SEAM(k) do { if (IN(k) && IN((k) + 1)) { if ((k) == 0) { cg::this_grid().sync(); bar = xcd_barrier_post(barw, MISC); } else { xcd_barrier(bar); } } } while (0)
; template <class Epi, class Sched, bool ALIGN_EPI = false, bool SP2 = false>
; __device__ __forceinline__ void gemm_phase(PG8_LAS unsigned char* lds, const Gemm g, const Sched& S, const Epi& E) {
;     ...
;     if (!S.next(0, cur)) return;
; __global__ void __launch_bounds__(NTHR, 2) fwd(Args args) {
;     ...
;     if (IN(12)) { gemm_res_ln(F, XB, WOUT, DM, F.out, F.in[10], F.in[11]); } SEAM(12);
.LBB0_1251:
	s_cmp_lt_i32 s80, 13
	s_cselect_b64 s[4:5], -1, 0
	s_and_b64 s[4:5], s[4:5], s[0:1]
	s_andn2_b64 vcc, exec, s[4:5]
	s_cbranch_vccnz .LBB0_1276
	s_cmpk_gt_i32 s84, 0x1ff
	v_readfirstlane_b32 s12, v146
	s_cbranch_scc1 .LBB0_1276
	s_bitcmp1_b32 s84, 2
	s_cbranch_scc0 .Lstag12_done
	s_memrealtime s[98:99]
	s_waitcnt lgkmcnt(0)
	s_mov_b32 s100, s98

; #define SEAM(k) do { if (IN(k) && IN((k) + 1)) { if ((k) == 0) { cg::this_grid().sync(); bar = xcd_barrier_post(barw, MISC); } else { xcd_barrier(bar); } } } while (0)
; template <class Epi, class Sched, bool ALIGN_EPI = false, bool SP2 = false>
; __device__ __forceinline__ void gemm_phase(PG8_LAS unsigned char* lds, const Gemm g, const Sched& S, const Epi& E) {
;     ...
;     if (!S.next(0, cur)) return;
; __global__ void __launch_bounds__(NTHR, 2) fwd(Args args) {
;     ...
;     if (IN(14)) { gemm_bf16(F, XB, W1, DFF, DM, BIG, DFF, true); } SEAM(14);
.LBB0_1384:
	s_cmp_lt_i32 s80, 15
	s_cselect_b64 s[4:5], -1, 0
	s_and_b64 s[4:5], s[4:5], s[0:1]
	s_andn2_b64 vcc, exec, s[4:5]
	s_cbranch_vccnz .LBB0_1401
	s_cmpk_gt_i32 s84, 0x7ff
	v_readfirstlane_b32 s1, v146
	s_cbranch_scc1 .LBB0_1401
	s_bitcmp1_b32 s84, 2
	s_cbranch_scc0 .Lstag14_done
	s_memrealtime s[98:99]
	s_waitcnt lgkmcnt(0)
	s_mov_b32 s100, s98

; #define PG8_STAGE(bufoff, gbase, voff) do { _Pragma("unroll") for (int _i = 0; _i < 2; ++_i) \
;         __builtin_amdgcn_global_load_lds((const unsigned*)((const char*)(gbase) + (voff)[_i]), (PG8_LAS unsigned*)(lds + (bufoff) + ldsw + _i * 8192), 16, 0, 0); } while (0)
; #define PG8_WAIT_V(n) asm volatile("s_waitcnt vmcnt(" #n ")" ::: "memory")
; #define PG8_BAR __builtin_amdgcn_s_barrier()
; template <class Epi, class Sched, bool ALIGN_EPI = false, bool SP2 = false>
; __device__ __forceinline__ void gemm_phase(PG8_LAS unsigned char* lds, const Gemm g, const Sched& S, const Epi& E) {
;     const int tid = threadIdx.x, wid = __builtin_amdgcn_readfirstlane(tid >> 6), lane = tid & 63, wr = wid >> 2, wc = wid & 3, fr = lane & 15, fq = lane >> 4;
;     const int K = g.K, nt = K / BK;
;     unsigned voffA[2], voffB[2];
; #pragma unroll
;     for (int i = 0; i < 2; ++i) { int R, C; stage_rc(tid * 16 + i * 8192, R, C); const int Rb = Epi::PERM ? ((R & ~31) + perm32(R & 31)) : R;
;         voffA[i] = (unsigned)(R * K + C) * 2u; voffB[i] = (unsigned)(Rb * K + C) * 2u; }
;     const size_t kstep = (size_t)(BK * 2);
;     const size_t hstep = (size_t)HALF * K * 2;
;     const size_t tstep = 2 * hstep;
;     const unsigned ldsw = (unsigned)wid * 1024u;
;     const int aoff = lds_byte(wr * 64 + fr, fq * 8), boff = lds_byte(wc * 32 + fr, fq * 8);
;     ...
;     Unit cur, nxt; int ui = 0;
;     if (!S.next(0, cur)) return;
;     f32x4 acc[2][2][4][2];
; #pragma unroll
;     for (int a = 0; a < 2; ++a)
; #pragma unroll
;         for (int b = 0; b < 2; ++b)
; #pragma unroll
;             for (int m = 0; m < 4; ++m)
; #pragma unroll
;                 for (int n = 0; n < 2; ++n) acc[a][b][m][n] = (f32x4){0.f, 0.f, 0.f, 0.f};
;     bf16x8 At[4][2], B0[2][2], B1[2][2];
;     const char* cA = (const char*)g.A + (size_t)cur.pm * tstep; const char* cB = (const char*)g.Bt + (size_t)cur.pn * tstep;
;     S.a_ready(cur);
;     if constexpr (SP2) {
;         PG8_STAGE(PG8_SB(0, 0), cB, voffB); PG8_STAGE(PG8_SB(0, 1), cB + hstep, voffB); PG8_STAGE(PG8_SA(0, 0), cA, voffA); PG8_STAGE(PG8_SA(0, 1), cA + hstep, voffA);
;         if (wr == 1) PG8_BAR;
;         PG8_WAIT_V(2); PG8_BAR;
;         PG8_STAGE(PG8_SB(1, 0), cB + kstep, voffB); PG8_STAGE(PG8_SA(1, 0), cA + kstep, voffA); PG8_STAGE(PG8_SB(1, 1), cB + hstep + kstep, voffB);
;         PG8_WAIT_V(6); PG8_BAR;
.Lstag14_done:
	v_lshrrev_b32_e32 v0, 5, v146
	v_lshrrev_b32_e32 v2, 1, v146
	v_and_b32_e32 v0, 4, v0
	v_bfe_u32 v1, v146, 2, 2
	v_and_b32_e32 v11, 24, v2
	v_or3_b32 v0, v0, v1, v11
	v_lshlrev_b32_e32 v1, 4, v146
	s_waitcnt lgkmcnt(0)
	v_add_u32_e32 v8, 0x2000, v1
	v_lshrrev_b32_e32 v2, 7, v8
	s_movk_i32 s0, 0xe0
	v_and_b32_e32 v4, 32, v146
	v_and_or_b32 v3, v2, s0, v0
	v_bitop3_b32 v9, v1, v4, 48 bitop3:0x6c
	v_and_b32_e32 v10, 64, v146
	v_bfe_u32 v12, v146, 2, 4
	s_movk_i32 s0, 0xf0
	v_or_b32_e32 v1, v9, v10
	v_and_or_b32 v2, v2, s0, v12
	s_waitcnt vmcnt(0)
	v_lshl_or_b32 v130, v2, 12, v1
	v_lshrrev_b32_e32 v2, 3, v146
	s_movk_i32 s0, 0x60
	v_and_or_b32 v0, v2, s0, v0
	s_movk_i32 s0, 0x70
	s_ashr_i32 s19, s84, 31
	v_lshl_or_b32 v132, v0, 12, v1
	v_and_or_b32 v0, v2, s0, v12
	s_lshr_b32 s0, s19, 29
	s_add_i32 s0, s84, s0
	s_lshr_b32 s8, s1, 6
	s_ashr_i32 s6, s0, 3
	s_and_b32 s0, s0, -8
	s_lshr_b32 s10, s1, 8
	s_lshl_b32 s3, s8, 10
	s_sub_i32 s0, s84, s0
	s_cmp_lt_i32 s0, 0
	s_movk_i32 s33, 0x101
	s_cselect_b32 s7, s33, 0x100
	s_mul_i32 s0, s7, s0
	s_add_i32 s0, s0, s6
	s_ashr_i32 s6, s0, 31
	s_lshr_b32 s6, s6, 24
	s_add_i32 s6, s0, s6
	s_ashr_i32 s7, s6, 8
	s_and_b32 s6, s6, 0xffffff00
	s_sub_i32 s6, s0, s6
	s_sext_i32_i16 s0, s6
	s_bfe_u32 s0, s0, 0x3001c
	s_add_i32 s9, s6, s0
	s_sext_i32_i16 s0, s9
	s_and_b32 s9, s9, 0xfff8
	s_sub_i32 s6, s6, s9
	s_lshl_b32 s7, s7, 3
	s_sext_i32_i16 s6, s6
	s_lshr_b32 s0, s0, 3
	s_add_i32 s40, s7, s6
	s_ashr_i32 s41, s40, 31
	s_bfe_i64 s[12:13], s[0:1], 0x100000
	s_lshl_b64 s[6:7], s[40:41], 20
	s_lshl_b64 s[12:13], s[12:13], 20
	v_readlane_b32 s14, v231, 22
	v_readlane_b32 s15, v231, 23
	s_add_u32 s44, s14, s12
	s_addc_u32 s45, s15, s13
	s_add_i32 s41, s3, 0
	s_add_i32 m0, s41, 0x10000
	v_lshl_or_b32 v128, v3, 12, v1
	global_load_lds_dwordx4 v132, s[44:45]
	s_add_i32 m0, s41, 0x12000
	s_add_u32 s12, s44, 0x80000
	global_load_lds_dwordx4 v128, s[44:45]
	s_addc_u32 s13, s45, 0
	s_add_i32 m0, s41, 0x14000
	v_lshl_or_b32 v134, v0, 12, v1
	global_load_lds_dwordx4 v132, s[12:13]
	s_add_i32 m0, s41, 0x16000
	s_add_u32 s42, s96, s6
	s_addc_u32 s43, s97, s7
	s_add_i32 s48, s41, 0x2000
	global_load_lds_dwordx4 v128, s[12:13]
	s_mov_b32 m0, s41
	s_add_u32 s6, s42, 0x80000
	global_load_lds_dwordx4 v134, s[42:43]
	s_mov_b32 m0, s48
	s_addc_u32 s7, s43, 0
	s_add_i32 s49, s41, 0x4000
	global_load_lds_dwordx4 v130, s[42:43]
	s_mov_b32 m0, s49
	s_add_i32 s50, s41, 0x6000
	global_load_lds_dwordx4 v134, s[6:7]
	s_mov_b32 m0, s50
	v_mov_b32_e32 v133, 0
	global_load_lds_dwordx4 v130, s[6:7]
	v_mov_b32_e32 v129, v133
	v_mov_b32_e32 v135, v133
	v_mov_b32_e32 v131, v133
	s_cmp_eq_u32 s10, 1
	s_mov_b32 s51, 0
	v_lshl_add_u64 v[6:7], s[44:45], 0, v[132:133]
	v_lshl_add_u64 v[4:5], s[44:45], 0, v[128:129]
	v_lshl_add_u64 v[0:1], s[42:43], 0, v[134:135]
	s_cselect_b64 s[6:7], -1, 0
	s_cmp_lg_u32 s10, 1
	v_lshl_add_u64 v[2:3], s[42:43], 0, v[130:131]
	s_cbranch_scc1 .LBB0_1388
	s_barrier

; #define SEAM(k) do { if (IN(k) && IN((k) + 1)) { if ((k) == 0) { cg::this_grid().sync(); bar = xcd_barrier_post(barw, MISC); } else { xcd_barrier(bar); } } } while (0)
; template <class Epi, class Sched, bool ALIGN_EPI = false, bool SP2 = false>
; __device__ __forceinline__ void gemm_phase(PG8_LAS unsigned char* lds, const Gemm g, const Sched& S, const Epi& E) {
;     ...
;     if (!S.next(0, cur)) return;
; __global__ void __launch_bounds__(NTHR, 2) fwd(Args args) {
;     ...
;     if (IN(15)) { gemm_res_ln(F, BIG, W2, DFF, F.out, F.in[6] + DM, F.in[7] + DM); } SEAM(15);
.LBB0_1451:
	s_cmp_lt_i32 s80, 16
	s_cselect_b64 s[4:5], -1, 0
	s_and_b64 s[4:5], s[4:5], s[0:1]
	s_andn2_b64 vcc, exec, s[4:5]
	s_cbranch_vccnz .LBB0_1476
	s_cmpk_gt_i32 s84, 0x1ff
	v_readfirstlane_b32 s16, v146
	s_cbranch_scc1 .LBB0_1476
	s_bitcmp1_b32 s84, 2
	s_cbranch_scc0 .Lstag15_done
	s_memrealtime s[98:99]
	s_waitcnt lgkmcnt(0)
	s_mov_b32 s100, s98

;     __host__ __device__ bool next(int i, Unit& u) const {
;         const long L = (long)i * G + c; if (L >= nwg) return false;
;         int wgid = (int)L; { const int q = nwg / NXCD, r = nwg % NXCD, xcd = wgid % NXCD, off = wgid / NXCD; wgid = (xcd < r ? xcd * (q + 1) : r * (q + 1) + (xcd - r) * q) + off; }
;         const int nig = WGM * nN, gid = wgid / nig, fm = gid * WGM, gsz = (nM - fm) < WGM ? (nM - fm) : WGM;
;         u.pm = fm + ((wgid % nig) % gsz); u.pn = (wgid % nig) / gsz; return true;
.Lstag15_done:
	s_ashr_i32 s3, s84, 31
	s_lshr_b32 s0, s3, 29
	s_add_i32 s8, s84, s0
	s_and_b32 s0, s8, -8
	s_sub_i32 s7, s84, s0
	s_cmp_gt_i32 s7, -1
	s_cbranch_scc0 .LBB0_1455
	s_lshl_b32 s6, s7, 6
	s_ashr_i32 s0, s8, 3
	s_cbranch_execz .LBB0_1456
	s_branch .LBB0_1457
